# cvhost pre-barrier: hosted item setup and load address prep also moved into the barrier-arrival window; only the three hosted loads stay behind the tile DMA; strict waits
# speedup vs baseline: 1.0010x; 1.0010x over previous
; template <class F>
; __device__ __forceinline__ void p0_item_fast(const float* W, int Nsrc, bf16_t* WT, int ldt, const float* ks, float gs, LAS float*  , int kb, int nb, int lane, F srccol) {
;     const int k0 = 64 * kb, n0 = 32 * nb, kk = lane >> 3, n4 = (lane & 7) * 4;
;     const int sc = srccol(n0 + n4);
;     const float* src = W + (size_t)(k0 + 8 * kk) * Nsrc + sc;
.Lcv_s2done:
.Lcv_prep:
	v_and_b32_e32 v76, 63, v0
	v_lshrrev_b32_e32 v77, 2, v76
	v_and_b32_e32 v78, 3, v76
	v_lshlrev_b32_e32 v78, 4, v78
	v_mad_u32_u24 v79, v77, s90, v78
	v_lshlrev_b32_e32 v80, 2, v77
.Lcv_prepdone:
	v_lshl_add_u64 v[112:113], s[28:29], 0, v[146:147]
	s_mov_b64 s[54:55], 0x18fc0000
	s_mov_b32 m0, s78
	v_lshl_add_u64 v[100:101], v[112:113], 0, s[54:55]
	s_add_i32 s98, s87, -1
	s_cmp_gt_u32 s98, 19
	s_cbranch_scc1 .Lcv_wa0
	s_waitcnt vmcnt(2)
	s_branch .Lcv_wad

; #define DMA_K(t, bf) do { if (ABL & 8) break; const char* kb_ = Kt + (size_t)(t) * KSTEP; LAS unsigned char* kd_ = Kl + (bf) * SHM_K + wid * 1024; \
;     glds16(kb_ + voffK, kd_); glds16(kb_ + 128 + voffK, kd_ + 8192); glds16(Pt + (size_t)(t) * PSTEP + voffP, kd_ + 16384); } while (0)
; #define DMA_V(t, bf) do { if (ABL & 8) break; const char* vb_ = Kt + 256 + (size_t)(t) * KSTEP; LAS unsigned char* vd_ = Vl + (bf) * SHM_V + wid * 1024; \
;     glds16(vb_ + voffV, vd_); glds16(vb_ + (size_t)32 * LDKV * 2 + voffV, vd_ + 8192); } while (0)
; template <int ABL> __device__ __forceinline__ void attn_unit(int b, int h, int qb, const bf16_t* Q, const bf16_t* KV, const bf16_t* KPE, bf16_t* MG, float* ssqa, LAS unsigned char* L) {
;     ...
;   DMA_K(0, 0); DMA_V(0, 0); DMA_K(1, 1);
; template <int NB>
; __device__ __forceinline__ void p0_batch(int it0, int stride, int lane, const P0Ptrs& a) {
;     ...
;     for (int q = 0; q < NB; ++q) { const bool ok = it0 < NFAST / 4; d[q] = p0_desc(p0_super(ok ? it0 : 0, q), lane, a); if (!ok) d[q].dst = nullptr;
; #pragma unroll
;         for (int i = 0; i < 8; ++i) v[q][i] = __builtin_nontemporal_load((const f32x4*)(d[q].src + (size_t)i * d[q].nsrc));
;         const float* kp = d[q].ks ? d[q].ks : a.ffn_g;
;         s0[q] = *(const f32x4*)(kp); s1[q] = *(const f32x4*)(kp + 4); }
.Lcv_wad:
	s_barrier
	global_load_lds_dwordx4 v[100:101], off
	v_lshl_add_u64 v[100:101], v[112:113], 0, s[38:39]
	s_add_i32 m0, s78, 0x2000
	v_lshl_add_u64 v[136:137], s[28:29], 0, v[144:145]
	global_load_lds_dwordx4 v[100:101], off
	v_lshl_add_u64 v[100:101], v[136:137], 0, s[40:41]
	s_add_i32 m0, s78, 0x4000
	v_lshl_add_u64 v[134:135], s[28:29], 0, v[148:149]
	global_load_lds_dwordx4 v[100:101], off
	v_lshl_add_u64 v[100:101], v[134:135], 0, s[42:43]
	s_mov_b32 m0, s58
	global_load_lds_dwordx4 v[100:101], off
	v_lshl_add_u64 v[100:101], v[134:135], 0, s[44:45]
	s_mov_b32 m0, s77
	global_load_lds_dwordx4 v[100:101], off
	s_cmp_gt_u32 s87, 20
	s_cbranch_scc1 .Lcv_done
	s_cmp_gt_u32 s87, 19
	s_cbranch_scc1 .Lcv_inc
	s_lshl_b32 s98, s90, 4
	global_load_dwordx4 v[238:241], v79, s[88:89] nt
	global_load_dwordx4 v[242:245], v79, s[88:89] offset:64 nt
	global_load_dword v237, v80, s[94:95]
	s_add_u32 s88, s88, s98
	s_addc_u32 s89, s89, 0
	s_add_u32 s94, s94, 64
	s_addc_u32 s95, s95, 0
	s_and_b32 s98, s87, 3
	s_cmp_lg_u32 s98, 3
	s_cbranch_scc1 .Lcv_inc
	s_cmp_gt_u32 s87, 18
	s_cbranch_scc1 .Lcv_inc
	s_add_i32 s99, s32, 1
	s_movk_i32 s98, 0x78
	s_cmp_lt_u32 s99, 7
	s_cselect_b32 s98, 0x60, s98
	s_cmp_eq_u32 s99, 0
	s_cselect_b32 s98, 0x50, s98
	s_cselect_b32 s99, 0, 0x58
	s_load_dwordx2 s[88:89], s[100:101], s98
	s_cmp_eq_u32 s99, 0
	s_cbranch_scc0 .Lcv_s1b_s
	s_bfe_u32 s99, s2, 0x50003
	s_cmp_lt_u32 s99, 16
	s_cselect_b32 s99, 64, 0x48
